# grid barrier: the arriving/polling wave runs at s_setprio 3 from barrier entry to the merge point
# baseline (speedup 1.0000x reference)
; #define LAS __attribute__((address_space(3)))
; template <typename T> DI volatile LAS T* lds_fresh(volatile LAS T* q) { asm volatile("" : "+v"(q)); return q; }
; DI unsigned xb_ld(unsigned* p) { return __hip_atomic_load(p, __ATOMIC_RELAXED, __HIP_MEMORY_SCOPE_AGENT); }
; DI void xcd_barrier_complete(unsigned* bar, unsigned x, unsigned& nloc, unsigned& nx) {
;   const unsigned G = gridDim.x * gridDim.y * gridDim.z;
;   unsigned sum, cnt, mine, sp = 0u;
;   for (;;) {
;     sum = 0u; cnt = 0u; mine = 0u;
; #pragma unroll
;     for (unsigned j = 0; j < 16; ++j) { const unsigned c = xb_ld(&bar[XB_XCNT(j)]); sum += c; cnt += (c > 0u) ? 1u : 0u; mine = (j == x) ? c : mine; }
;     if (sum == G) break;
;     __builtin_amdgcn_s_sleep(1);
;     if ((++sp & 255u) == 0u) { if (xb_ld(&bar[XB_TMO])) break; if (sp > XB_SPIN_CAP) { atomicAdd(&bar[XB_TMO], 1u); break; } }
;   }
;   nloc = mine > 0u ? mine : 1u; nx = cnt > 0u ? cnt : 1u;
; }
; DI void xcd_barrier(const XcdBarrier& b) {
;   asm volatile("s_waitcnt vmcnt(0)" ::: "memory");
;   __syncthreads();
;   if (tid_now(b.wv) == 0) {
;     unsigned* bar = b.bar;
;     __builtin_amdgcn_s_waitcnt(0);
;     volatile LAS unsigned* st = lds_fresh(b.st);
;     unsigned nloc = st[0], nx = st[1];
;     if (nloc == 0u) { xcd_barrier_complete(bar, b.x, nloc, nx); st[0] = nloc; st[1] = nx; }
.LBB0_54:
	s_or_b64 exec, exec, s[0:1]
	s_mul_i32 s0, s87, s86
	s_mul_i32 s23, s0, s18
	s_add_u32 s0, s80, 0x200
	s_addc_u32 s1, s81, 0
	s_add_u32 s26, s80, 0x1000
	s_addc_u32 s27, s81, 0
	s_add_u32 s12, s80, 0x1100
	s_addc_u32 s13, s81, 0
	s_add_u32 s14, s80, 0x1200
	s_addc_u32 s15, s81, 0
	s_add_u32 s20, s80, 0x1300
	s_addc_u32 s21, s81, 0
	v_writelane_b32 v251, s0, 17
	s_cmp_eq_u32 s3, 15
	s_waitcnt vmcnt(0)
	s_waitcnt lgkmcnt(0)
	v_writelane_b32 v251, s1, 18
	s_cselect_b64 s[0:1], -1, 0
	v_writelane_b32 v251, s0, 19
	s_cmp_eq_u32 s3, 14
	s_barrier
	v_writelane_b32 v251, s1, 20
	s_cselect_b64 s[0:1], -1, 0
	v_writelane_b32 v251, s0, 21
	s_cmp_eq_u32 s3, 13
	s_nop 0
	v_writelane_b32 v251, s1, 22
	s_cselect_b64 s[0:1], -1, 0
	v_writelane_b32 v251, s0, 23
	s_cmp_eq_u32 s3, 12
	v_mbcnt_lo_u32_b32 v0, -1, 0
	v_mbcnt_hi_u32_b32 v0, -1, v0
	s_nop 0
	v_writelane_b32 v251, s1, 24
	s_cselect_b64 s[0:1], -1, 0
	v_writelane_b32 v251, s0, 25
	s_cmp_eq_u32 s3, 11
	v_cmp_eq_u32_e32 vcc, s41, v0
	v_writelane_b32 v251, s1, 26
	s_cselect_b64 s[0:1], -1, 0
	v_writelane_b32 v251, s0, 27
	s_cmp_eq_u32 s3, 10
	s_nop 0
	v_writelane_b32 v251, s1, 28
	s_cselect_b64 s[0:1], -1, 0
	v_writelane_b32 v251, s0, 29
	s_cmp_eq_u32 s3, 9
	s_nop 0
	v_writelane_b32 v251, s1, 30
	s_cselect_b64 s[0:1], -1, 0
	v_writelane_b32 v251, s0, 31
	s_cmp_eq_u32 s3, 8
	s_nop 0
	v_writelane_b32 v251, s1, 32
	s_cselect_b64 s[0:1], -1, 0
	v_writelane_b32 v251, s0, 33
	s_cmp_eq_u32 s3, 7
	s_nop 0
	v_writelane_b32 v251, s1, 34
	s_cselect_b64 s[0:1], -1, 0
	v_writelane_b32 v251, s0, 35
	s_cmp_eq_u32 s3, 6
	s_nop 0
	v_writelane_b32 v251, s1, 36
	s_cselect_b64 s[0:1], -1, 0
	v_writelane_b32 v251, s0, 37
	s_cmp_eq_u32 s3, 5
	s_nop 0
	v_writelane_b32 v251, s1, 38
	s_cselect_b64 s[0:1], -1, 0
	v_writelane_b32 v251, s0, 39
	s_cmp_eq_u32 s3, 4
	s_nop 0
	v_writelane_b32 v251, s1, 40
	s_cselect_b64 s[0:1], -1, 0
	v_writelane_b32 v251, s0, 41
	s_cmp_eq_u32 s3, 3
	s_nop 0
	v_writelane_b32 v251, s1, 42
	s_cselect_b64 s[0:1], -1, 0
	v_writelane_b32 v251, s0, 43
	s_cmp_eq_u32 s3, 2
	s_nop 0
	v_writelane_b32 v251, s1, 44
	s_cselect_b64 s[0:1], -1, 0
	v_writelane_b32 v251, s0, 45
	s_cmp_eq_u32 s3, 1
	s_nop 0
	v_writelane_b32 v251, s1, 46
	s_cselect_b64 s[0:1], -1, 0
	v_writelane_b32 v251, s0, 47
	s_cmp_eq_u32 s3, 0
	s_nop 0
	v_writelane_b32 v251, s1, 48
	s_cselect_b64 s[0:1], -1, 0
	v_writelane_b32 v251, s0, 49
	s_nop 1
	v_writelane_b32 v251, s1, 50
	s_lshl_b32 s0, s3, 8
	s_add_u32 s0, s80, s0
	s_addc_u32 s1, s81, 0
	s_add_u32 s4, s0, 0x1400
	s_addc_u32 s5, s1, 0
	v_writelane_b32 v251, s4, 51
	s_add_u32 s0, s0, 0x2400
	s_addc_u32 s1, s1, 0
	v_writelane_b32 v251, s5, 52
	v_writelane_b32 v251, s0, 53
	s_nop 1
	v_writelane_b32 v251, s1, 54
	s_add_u32 s0, s80, 0x3400
	s_addc_u32 s1, s81, 0
	v_writelane_b32 v251, s0, 55
	s_nop 1
	v_writelane_b32 v251, s1, 56
	s_add_u32 s0, s80, 0x3500
	s_addc_u32 s1, s81, 0
	v_writelane_b32 v251, s0, 57
	s_nop 1
	v_writelane_b32 v251, s1, 58
	s_and_saveexec_b64 s[0:1], vcc
	v_writelane_b32 v251, s12, 59
	s_nop 1
	v_writelane_b32 v251, s13, 60
	v_writelane_b32 v251, s14, 61
	s_nop 1
	v_writelane_b32 v251, s15, 62
	s_cbranch_execz .LBB0_106
	v_mov_b32_e32 v1, 0x12010
	s_waitcnt vmcnt(0) expcnt(0) lgkmcnt(0)
	s_setprio 3
	ds_read_b32 v2, v1
	ds_read_b32 v0, v1 offset:4
	s_waitcnt lgkmcnt(1)
	v_cmp_eq_u32_e32 vcc, 0, v2
	s_and_saveexec_b64 s[4:5], vcc
	s_cbranch_execz .LBB0_70
	s_mov_b32 s3, 1
	v_mov_b32_e32 v17, 0
	s_branch .LBB0_58

; #define LAS __attribute__((address_space(3)))
; DI void attn_item_A(const Params& p, int layer, int b, int head, int qb, u16* sm, float lam, float lam_init, int wv) {
;   const int tid = tid_now(wv), lane = tid & 63, w = tid >> 6, r = lane & 31, h = lane >> 5;
;   const int qsub = w & 1, kh = w >> 1;
;   const int q0 = qb * 64, q0w = q0 + 32 * qsub, qpos = q0w + r;
;   const int qoff = head * 64, koff = 256 + head * 64, vh = head, goff = 768 + head * 64, yoff = head * 64;
;   const u16* projb = p.proj + (size_t)b * SEQ * DIN;
;   u16* Kb0 = sm + kh * (4 * 64 * 64);
;   bf16x8 qf[4];
; #pragma unroll
;   for (int ks = 0; ks < 4; ++ks) qf[ks] = __builtin_nontemporal_load((const bf16x8*)(projb + (size_t)qpos * DIN + qoff + 16 * ks + 8 * h));
;   const float sl2 = exp2f(-8.f * (float)(9 + head) / 12.f) * LOG2E;
; __global__ void __launch_bounds__(256, 2) hymba_mega(Params p) {
;     ...
;   const int wv = __builtin_amdgcn_readfirstlane((int)threadIdx.x >> 6);
;   const int bid = blockIdx.x, nb = gridDim.x;
;   const int xcd = bid & 7, lb = bid >> 3, nxb = nb >> 3;
;   __shared__ __attribute__((aligned(16))) unsigned xb_words[4];
;   if (tid_now(wv) == 0) { xb_words[0] = 0u; xb_words[1] = 0u; xb_words[2] = 0u; xb_words[3] = 0u; }
;   __syncthreads();
;   const XcdBarrier gb = xcd_barrier_post(p.bar, (volatile LAS unsigned*)xb_words, wv);
;   if (p.never) grid.sync();
;   for (int rep = 0; rep < REP_PREP; ++rep) { phase_prep(p, sm, wv); xcd_barrier(gb); }
;   for (int layer = 0; layer < DEPTH; ++layer) {
;     for (int rep = 0; rep < REP_G0; ++rep) {
;       for (int u = lb; u < 8 * 26; u += nxb) gemm_tile<0>(p, layer, xcd + 8 * (u & 7), u >> 3, sm, wv);
.LBB0_106:
	s_setprio 0
	v_writelane_b32 v251, s22, 63
	s_nop 1
	v_writelane_b32 v250, s23, 0
	s_or_b64 exec, exec, s[0:1]
	s_and_b32 s22, s2, 7
	s_ashr_i32 s28, s2, 3
	s_ashr_i32 s97, s86, 3
	s_cmpk_lt_i32 s28, 0xd0
	s_cselect_b64 s[0:1], -1, 0
	v_writelane_b32 v250, s0, 1
	s_mov_b32 s5, 0x41400000
	v_mov_b32_e32 v187, 0x42800000
	v_writelane_b32 v250, s1, 2
	s_lshl_b32 s0, s22, 2
	s_add_u32 s0, s94, s0
	v_writelane_b32 v250, s0, 3
	s_addc_u32 s0, s95, 0
	v_writelane_b32 v250, s0, 4
	s_lshl_b32 s0, s2, 1
	s_bfe_u32 s1, s2, 0x10002
	s_and_b32 s0, s0, 6
	v_writelane_b32 v250, s0, 5
	s_lshl_b32 s6, s1, 13
	s_mul_i32 s0, s1, 0x3400000
	s_add_u32 s8, s62, s0
	s_addc_u32 s9, s63, 0
	s_mul_i32 s3, s1, 10
	s_and_b32 s2, s2, 3
	s_add_i32 s0, s3, 4
	s_lshl_b32 s4, s2, 7
	v_writelane_b32 v250, s0, 6
	s_add_u32 s30, s8, s4
	v_writelane_b32 v250, s8, 7
	s_addc_u32 s31, s9, 0
	s_lshl_b32 s0, s2, 3
	s_xor_b32 s0, s0, 0xffffffb8
	s_waitcnt lgkmcnt(0)
	v_cvt_f32_i32_e32 v0, s0
	s_mov_b32 s94, 0xc2fc0000
	s_mov_b32 s37, 0
	v_writelane_b32 v250, s9, 8
	v_div_scale_f32 v1, s[0:1], s5, s5, v0
	v_rcp_f32_e32 v2, v1
	s_mov_b32 s7, s37
	v_writelane_b32 v250, s6, 9
	s_mov_b32 s50, 0x41c00000
	v_fma_f32 v3, -v1, v2, 1.0
	v_fmac_f32_e32 v2, v3, v2
	v_div_scale_f32 v3, vcc, v0, s5, v0
	v_mul_f32_e32 v4, v3, v2
	v_fma_f32 v5, -v1, v4, v3
	v_fmac_f32_e32 v4, v5, v2
	v_fma_f32 v1, -v1, v4, v3
	v_div_fmas_f32 v1, v1, v2, v4
	v_div_fixup_f32 v0, v1, s5, v0
	v_cmp_gt_f32_e32 vcc, s94, v0
	s_and_b64 s[0:1], vcc, exec
	s_cselect_b32 s0, 0xffffffc0, 0
	v_cndmask_b32_e32 v1, 0, v187, vcc
	v_add_f32_e32 v0, v0, v1
	v_exp_f32_e32 v0, v0
	s_add_i32 s3, s3, s2
	v_writelane_b32 v250, s7, 10
	s_mov_b32 s72, 0x42280000
	v_ldexp_f32 v0, v0, s0
	s_lshl_b32 s0, s3, 20
	s_add_u32 s2, s88, s0
	s_addc_u32 s3, s89, 0
	v_writelane_b32 v250, s2, 11
	v_mul_f32_e32 v178, 0x3fb8aa3b, v0
	s_mov_b32 s74, 0x42200000
	v_writelane_b32 v250, s3, 12
	s_add_u32 s2, s90, s4
	v_readlane_b32 s4, v251, 0
	s_addc_u32 s3, s91, 0
	v_readlane_b32 s18, v251, 14
	v_readlane_b32 s19, v251, 15
	v_writelane_b32 v250, s2, 13
	s_cmp_lg_u64 s[18:19], 0
	v_readlane_b32 s10, v251, 6
	v_writelane_b32 v250, s3, 14
	s_cselect_b64 s[2:3], -1, 0
	s_add_i32 s0, s0, 0x600000
	v_writelane_b32 v250, s2, 15
	s_add_u32 s0, s88, s0
	s_addc_u32 s1, s89, 0
	v_writelane_b32 v250, s3, 16
	v_writelane_b32 v250, s0, 17
	v_readlane_b32 s11, v251, 7
	v_readlane_b32 s12, v251, 8
	v_writelane_b32 v250, s1, 18
	s_add_u32 s0, s30, 0x1400
	v_writelane_b32 v250, s30, 19
	s_addc_u32 s1, s31, 0
	s_cmp_lt_i32 s28, 64
	v_writelane_b32 v250, s31, 20
	v_writelane_b32 v250, s0, 21
	v_readlane_b32 s13, v251, 9
	v_readlane_b32 s14, v251, 10
	v_writelane_b32 v250, s1, 22
	v_writelane_b32 v250, s28, 23
	s_cselect_b64 s[0:1], -1, 0
	v_writelane_b32 v250, s0, 24
	v_readlane_b32 s15, v251, 11
	v_readlane_b32 s8, v251, 4
	v_writelane_b32 v250, s1, 25
	s_mov_b32 s0, s37
	v_writelane_b32 v250, s0, 26
	v_readlane_b32 s9, v251, 5
	s_mov_b32 s28, 0x41d00000
	v_writelane_b32 v250, s1, 27
	s_mov_b32 s30, 0x42600000
	s_mov_b32 s10, 0x42480000
	s_mov_b32 s76, 0x42080000
	s_mov_b32 s78, 0x42000000
	v_writelane_b32 v250, s41, 28
	v_readlane_b32 s12, v251, 59
	v_readlane_b32 s14, v251, 61
	v_mov_b32_e32 v179, v178
	s_mov_b32 s67, 0x20000
	s_mov_b32 s66, 0x80000
	v_mov_b32_e32 v188, 0x3727c5ac
	v_mov_b32_e32 v1, 0
	v_mov_b32_e32 v189, 1
	v_mov_b32_e32 v190, 0x3f4ccccd
	s_mov_b32 s51, 0x41c80000
	s_mov_b32 s29, 0x41d80000
	s_mov_b32 s31, 0x42640000
	s_mov_b32 s11, 0x424c0000
	s_mov_b32 s73, 0x422c0000
	s_mov_b32 s75, 0x42240000
	s_mov_b32 s77, 0x420c0000
	s_mov_b32 s79, 0x42040000
	v_mov_b32_e32 v191, 0x3e38aa3b
	v_mov_b32_e32 v192, 0x3e8293ee
	v_mov_b32_e32 v193, 0x61800
	v_mov_b32_e32 v194, 0x78000
	v_mov_b32_e32 v195, 0x7f800000
	v_mov_b32_e32 v196, 0xc0
	v_mov_b32_e32 v197, 0x80
	v_mov_b32_e32 v198, 0x42fc0000
	v_mov_b32_e32 v199, 0xff800000
	v_mov_b32_e32 v200, 0x10e00
	v_mov_b32_e32 v201, 0x3f803f80
	s_movk_i32 s24, 0x50
	s_movk_i32 s95, 0x80
	s_movk_i32 s8, 0x1a00
	s_mov_b32 s9, 0x5368d4a5
	s_mov_b64 s[34:35], -1
	s_mov_b64 s[68:69], 0x200
	s_mov_b32 s25, 0
	s_mov_b32 s86, 0x40000
	s_mov_b32 s96, 0x3f803f80
	v_readlane_b32 s13, v251, 60
	v_readlane_b32 s15, v251, 62
	v_writelane_b32 v250, s97, 29
	s_barrier
	v_readlane_b32 s5, v251, 1
	v_readlane_b32 s6, v251, 2
	v_readlane_b32 s7, v251, 3
	v_readlane_b32 s16, v251, 12
	v_readlane_b32 s17, v251, 13
	v_writelane_b32 v250, s22, 30
	s_branch .LBB0_109

; __global__ void __launch_bounds__(256, 2) hymba_mega(Params p) {
;     ...
;     xcd_barrier(gb);
;     for (int u = lb; u < 8 * 8; u += nxb) gemm_tile<1>(p, layer, xcd + 8 * (u & 7), u >> 3, sm, wv);
;     xcd_barrier(gb);
;   }
.LBB0_108:
	s_setprio 0
	s_or_b64 exec, exec, s[0:1]
	s_mov_b32 s0, 1
	v_writelane_b32 v250, s0, 26
	s_mov_b64 s[34:35], 0
	s_and_b64 vcc, exec, s[70:71]
	s_waitcnt lgkmcnt(0)
	s_barrier
	v_writelane_b32 v250, s1, 27
	s_cbranch_vccnz .LBB0_522

; #define LAS __attribute__((address_space(3)))
; template <typename T> DI volatile LAS T* lds_fresh(volatile LAS T* q) { asm volatile("" : "+v"(q)); return q; }
; DI void xcd_barrier(const XcdBarrier& b) {
;   asm volatile("s_waitcnt vmcnt(0)" ::: "memory");
;   __syncthreads();
;   if (tid_now(b.wv) == 0) {
;     unsigned* bar = b.bar;
;     __builtin_amdgcn_s_waitcnt(0);
;     volatile LAS unsigned* st = lds_fresh(b.st);
;     unsigned nloc = st[0], nx = st[1];
;     if (nloc == 0u) { xcd_barrier_complete(bar, b.x, nloc, nx); st[0] = nloc; st[1] = nx; }
.LBB0_141:
	s_waitcnt vmcnt(0)
	s_barrier
	v_mbcnt_lo_u32_b32 v0, -1, 0
	v_mbcnt_hi_u32_b32 v0, -1, v0
	s_nop 0
	v_cmp_eq_u32_e32 vcc, s41, v0
	s_and_saveexec_b64 s[0:1], vcc
	s_cbranch_execz .LBB0_193
	v_mov_b32_e32 v3, 0x12010
	s_waitcnt vmcnt(0) expcnt(0) lgkmcnt(0)
	s_setprio 3
	ds_read_b32 v2, v3
	ds_read_b32 v0, v3 offset:4
	s_waitcnt lgkmcnt(1)
	v_cmp_eq_u32_e32 vcc, 0, v2
	s_and_saveexec_b64 s[2:3], vcc
	s_cbranch_execz .LBB0_157
	s_mov_b64 s[20:21], s[44:45]
	s_mov_b32 s18, 1
	s_branch .LBB0_145

; __global__ void __launch_bounds__(256, 2) hymba_mega(Params p) {
;     ...
;       const float lam_init = 0.8f - 0.6f * expf(-0.3f * (float)layer);
;       float d1 = 0.f, d2 = 0.f;
;       for (int i = 0; i < 32; ++i) {
;         d1 += p.lq1[layer * 32 + i] * p.lk1[layer * 32 + i];
;         d2 += p.lq2[layer * 32 + i] * p.lk2[layer * 32 + i];
;       }
;       const float lam = expf(d1) - expf(d2) + lam_init;
.LBB0_193:
	s_setprio 0
	v_readlane_b32 s2, v251, 17
	v_readlane_b32 s3, v251, 18
	s_or_b64 exec, exec, s[0:1]
	v_readlane_b32 s64, v250, 26
	s_mov_b64 s[42:43], s[26:27]
	s_mov_b32 s36, s23
	s_waitcnt lgkmcnt(0)
	v_cvt_f32_u32_e32 v0, s64
	s_mov_b32 s37, 0x3fb8aa3b
	s_mov_b32 s39, s25
	s_lshl_b32 s38, s64, 5
	v_mul_f32_e32 v0, 0xbe99999a, v0
	v_mul_f32_e32 v2, 0x3fb8aa3b, v0
	v_readlane_b32 s12, v251, 0
	s_xor_b64 s[70:71], s[34:35], -1
	v_fma_f32 v3, v0, s37, -v2
	v_rndne_f32_e32 v4, v2
	s_lshl_b64 s[4:5], s[38:39], 2
	v_readlane_b32 s18, v251, 6
	v_fmac_f32_e32 v3, 0x32a5705f, v0
	v_sub_f32_e32 v2, v2, v4
	v_readlane_b32 s19, v251, 7
	s_add_u32 s6, s18, s4
	v_add_f32_e32 v2, v2, v3
	v_readlane_b32 s20, v251, 8
	s_addc_u32 s7, s19, s5
	v_exp_f32_e32 v2, v2
	v_cvt_i32_f32_e32 v3, v4
	v_readlane_b32 s21, v251, 9
	s_add_u32 s2, s20, s4
	v_readlane_b32 s22, v251, 10
	s_addc_u32 s3, s21, s5
	v_readlane_b32 s23, v251, 11
	s_add_u32 s0, s22, s4
	s_mov_b32 s40, 0xc2ce8ed0
	v_readlane_b32 s24, v251, 12
	s_addc_u32 s1, s23, s5
	v_ldexp_f32 v2, v2, v3
	v_cmp_ngt_f32_e32 vcc, s40, v0
	s_mov_b32 s46, 0x42b17218
	v_readlane_b32 s25, v251, 13
	s_add_u32 s4, s24, s4
	v_cndmask_b32_e32 v2, 0, v2, vcc
	v_cmp_nlt_f32_e32 vcc, s46, v0
	s_addc_u32 s5, s25, s5
	s_barrier
	v_cndmask_b32_e32 v0, v195, v2, vcc
	global_load_dwordx4 v[2:5], v1, s[6:7] offset:48
	global_load_dwordx4 v[6:9], v1, s[6:7] offset:32
	global_load_dwordx4 v[10:13], v1, s[6:7] offset:16
	global_load_dwordx4 v[14:17], v1, s[6:7]
	global_load_dwordx4 v[18:21], v1, s[2:3] offset:48
	global_load_dwordx4 v[22:25], v1, s[2:3] offset:32
	global_load_dwordx4 v[26:29], v1, s[2:3] offset:16
	global_load_dwordx4 v[30:33], v1, s[2:3]
	global_load_dwordx4 v[34:37], v1, s[0:1] offset:48
	global_load_dwordx4 v[38:41], v1, s[0:1] offset:32
	global_load_dwordx4 v[42:45], v1, s[0:1] offset:16
	global_load_dwordx4 v[46:49], v1, s[0:1]
	global_load_dwordx4 v[52:55], v1, s[4:5] offset:48
	global_load_dwordx4 v[56:59], v1, s[4:5] offset:32
	global_load_dwordx4 v[60:63], v1, s[4:5] offset:16
	global_load_dwordx4 v[64:67], v1, s[4:5]
	s_lshl_b32 s38, s64, 3
	v_readlane_b32 s26, v251, 14
	v_readlane_b32 s65, v250, 27
	v_readlane_b32 s13, v251, 1
	v_readlane_b32 s14, v251, 2
	v_readlane_b32 s15, v251, 3
	v_readlane_b32 s27, v251, 15
	v_fmamk_f32 v0, v0, 0xbf19999a, v190
	v_readlane_b32 s12, v251, 59
	v_readlane_b32 s14, v251, 61
	v_sub_f32_e32 v203, 1.0, v0
	s_mov_b64 s[24:25], s[38:39]
	s_mov_b64 s[84:85], 0
	s_mov_b32 s23, s36
	v_readlane_b32 s13, v251, 60
	v_readlane_b32 s15, v251, 62
	s_mov_b64 s[20:21], s[44:45]
	v_readlane_b32 s16, v251, 4
	v_readlane_b32 s17, v251, 5
	s_waitcnt vmcnt(8)
	v_fma_f32 v51, v14, v30, 0
	v_fmac_f32_e32 v51, v15, v31
	s_waitcnt vmcnt(0)
	v_fma_f32 v50, v46, v64, 0
	v_fmac_f32_e32 v50, v47, v65
	v_fmac_f32_e32 v51, v16, v32
	v_fmac_f32_e32 v50, v48, v66
	v_fmac_f32_e32 v51, v17, v33
	v_fmac_f32_e32 v50, v49, v67
	v_fmac_f32_e32 v51, v10, v26
	v_fmac_f32_e32 v50, v42, v60
	v_fmac_f32_e32 v51, v11, v27
	v_fmac_f32_e32 v50, v43, v61
	v_fmac_f32_e32 v51, v12, v28
	v_fmac_f32_e32 v50, v44, v62
	v_fmac_f32_e32 v51, v13, v29
	v_fmac_f32_e32 v50, v45, v63
	v_fmac_f32_e32 v51, v6, v22
	v_fmac_f32_e32 v50, v38, v56
	v_fmac_f32_e32 v51, v7, v23
	v_fmac_f32_e32 v50, v39, v57
	v_fmac_f32_e32 v51, v8, v24
	v_fmac_f32_e32 v50, v40, v58
	v_fmac_f32_e32 v51, v9, v25
	v_fmac_f32_e32 v50, v41, v59
	v_fmac_f32_e32 v51, v2, v18
	v_fmac_f32_e32 v50, v34, v52
	v_fmac_f32_e32 v51, v3, v19
	v_fmac_f32_e32 v50, v35, v53
	v_fmac_f32_e32 v51, v4, v20
	v_fmac_f32_e32 v50, v36, v54
	v_fmac_f32_e32 v51, v5, v21
	v_fmac_f32_e32 v50, v37, v55
	global_load_dwordx4 v[2:5], v1, s[6:7] offset:112
	global_load_dwordx4 v[10:13], v1, s[6:7] offset:96
	global_load_dwordx4 v[18:21], v1, s[6:7] offset:80
	global_load_dwordx4 v[26:29], v1, s[6:7] offset:64
	global_load_dwordx4 v[6:9], v1, s[2:3] offset:112
	global_load_dwordx4 v[14:17], v1, s[2:3] offset:96
	global_load_dwordx4 v[22:25], v1, s[2:3] offset:80
	global_load_dwordx4 v[52:55], v1, s[2:3] offset:64
	global_load_dwordx4 v[30:33], v1, s[0:1] offset:112
	global_load_dwordx4 v[38:41], v1, s[0:1] offset:96
	global_load_dwordx4 v[46:49], v1, s[0:1] offset:80
	global_load_dwordx4 v[56:59], v1, s[0:1] offset:64
	global_load_dwordx4 v[34:37], v1, s[4:5] offset:112
	global_load_dwordx4 v[42:45], v1, s[4:5] offset:96
	global_load_dwordx4 v[60:63], v1, s[4:5] offset:80
	global_load_dwordx4 v[64:67], v1, s[4:5] offset:64
	s_lshl_b64 s[0:1], s[38:39], 2
	v_readlane_b32 s2, v250, 3
	s_add_u32 s2, s2, s0
	v_readlane_b32 s0, v250, 4
	s_addc_u32 s3, s0, s1
	s_lshl_b32 s0, s64, 6
	s_mov_b32 s1, s39
	s_lshl_b64 s[0:1], s[0:1], 2
	v_writelane_b32 v250, s2, 31
	s_add_u32 s0, s26, s0
	s_addc_u32 s1, s27, s1
	v_writelane_b32 v250, s3, 32
	v_writelane_b32 v250, s0, 33
	s_mov_b64 s[26:27], s[42:43]
	s_waitcnt vmcnt(8)
	v_fmac_f32_e32 v51, v26, v52
	v_fmac_f32_e32 v51, v27, v53
	v_fmac_f32_e32 v51, v28, v54
	v_fmac_f32_e32 v51, v29, v55
	v_fmac_f32_e32 v51, v18, v22
	v_fmac_f32_e32 v51, v19, v23
	v_fmac_f32_e32 v51, v20, v24
	v_fmac_f32_e32 v51, v21, v25
	s_waitcnt vmcnt(0)
	v_fmac_f32_e32 v50, v56, v64
	v_fmac_f32_e32 v51, v10, v14
	v_fmac_f32_e32 v50, v57, v65
	v_fmac_f32_e32 v51, v11, v15
	v_fmac_f32_e32 v50, v58, v66
	v_fmac_f32_e32 v51, v12, v16
	v_fmac_f32_e32 v50, v59, v67
	v_fmac_f32_e32 v51, v13, v17
	v_fmac_f32_e32 v50, v46, v60
	v_fmac_f32_e32 v51, v2, v6
	v_fmac_f32_e32 v50, v47, v61
	v_fmac_f32_e32 v51, v3, v7
	v_fmac_f32_e32 v50, v48, v62
	v_fmac_f32_e32 v51, v4, v8
	v_fmac_f32_e32 v50, v49, v63
	v_fmac_f32_e32 v51, v5, v9
	v_fmac_f32_e32 v50, v38, v42
	v_mul_f32_e32 v2, 0x3fb8aa3b, v51
	v_fmac_f32_e32 v50, v39, v43
	v_fma_f32 v3, v51, s37, -v2
	v_rndne_f32_e32 v4, v2
	v_fmac_f32_e32 v50, v40, v44
	v_fmac_f32_e32 v3, 0x32a5705f, v51
	v_sub_f32_e32 v2, v2, v4
	v_fmac_f32_e32 v50, v41, v45
	v_add_f32_e32 v2, v2, v3
	v_fmac_f32_e32 v50, v30, v34
	v_exp_f32_e32 v2, v2
	v_cvt_i32_f32_e32 v3, v4
	v_fmac_f32_e32 v50, v31, v35
	v_fmac_f32_e32 v50, v32, v36
	v_fmac_f32_e32 v50, v33, v37
	v_ldexp_f32 v2, v2, v3
	v_mul_f32_e32 v3, 0x3fb8aa3b, v50
	v_fma_f32 v4, v50, s37, -v3
	v_rndne_f32_e32 v5, v3
	v_fmac_f32_e32 v4, 0x32a5705f, v50
	v_sub_f32_e32 v3, v3, v5
	v_add_f32_e32 v3, v3, v4
	v_exp_f32_e32 v3, v3
	v_cvt_i32_f32_e32 v4, v5
	v_cmp_ngt_f32_e32 vcc, s40, v51
	v_writelane_b32 v250, s1, 34
	v_ldexp_f32 v3, v3, v4
	v_cndmask_b32_e32 v2, 0, v2, vcc
	v_cmp_nlt_f32_e32 vcc, s46, v51
	s_nop 1
	v_cndmask_b32_e32 v2, v195, v2, vcc
	v_cmp_ngt_f32_e32 vcc, s40, v50
	s_nop 1
	v_cndmask_b32_e32 v3, 0, v3, vcc
	v_cmp_nlt_f32_e32 vcc, s46, v50
	s_nop 1
	v_cndmask_b32_e32 v3, v195, v3, vcc
	v_sub_f32_e32 v2, v2, v3
	v_add_f32_e32 v202, v0, v2
	v_mov_b32_e32 v253, 1
	v_mov_b32_e32 v254, 1
	s_branch .LBB0_198

; DI void attn_item_A(const Params& p, int layer, int b, int head, int qb, u16* sm, float lam, float lam_init, int wv) {
;     ...
;   auto dma_tile = [&](int T, int c) {
;     const int k0 = 64 * T;
;     u16* Kd = Kb0 + c * (2 * 64 * 64) + wp * (8 * 64);
; #pragma unroll
;     for (int i = 0; i < 4; ++i) {
;       __builtin_amdgcn_global_load_lds((const unsigned*)(kg + (size_t)(k0 + row0 + 16 * i) * DIN), (unsigned*)(Kd + i * 16 * 64), 16, 0, 0);
;       __builtin_amdgcn_global_load_lds((const unsigned*)(vg + (size_t)(row0 + 16 * i) * SEQ + k0), (unsigned*)(Kd + 64 * 64 + i * 16 * 64), 16, 0, 0);
;     }
;   };
;   if (v0) dma_tile(T0, 0);
;   asm volatile("" :: "v"(qf[0]), "v"(qf[1]), "v"(qf[2]), "v"(qf[3]));
;   asm volatile("s_waitcnt vmcnt(0)" ::: "memory");
;   __syncthreads();
;   for (int j = 0; j < npairs; ++j) {
;     if (j + 1 < npairs) dma_tile(T0 - 2 * (j + 1), (j + 1) & 1);
.LBB0_276:
	s_or_b64 exec, exec, s[18:19]
	s_waitcnt vmcnt(0)
	v_and_b32_e32 v205, 60, v125
	s_waitcnt vmcnt(0) lgkmcnt(0)
	s_barrier
	s_and_saveexec_b64 s[18:19], vcc
	s_cbranch_execz .LBB0_292
	v_add_u32_e32 v66, v120, v171
	v_sub_u32_e32 v66, v66, v124
	v_lshlrev_b32_e32 v67, 6, v118
	v_sub_u32_e32 v66, v66, v67
	v_lshlrev_b32_e32 v206, 6, v173
	v_lshlrev_b32_e32 v67, 6, v119
	v_sub_u32_e32 v66, v66, v206
	v_and_b32_e32 v67, 0xffffff80, v67
	v_sub_u32_e32 v66, v66, v67
	v_add_u32_e32 v207, 0x2040, v66
	v_add_u32_e32 v66, v118, v173
	s_movk_i32 s2, 0xff7f
	v_add3_u32 v208, v66, v123, s2
	v_or_b32_e32 v66, v121, v67
	v_cmp_gt_u32_e64 s[36:37], 16, v171
	v_add_u32_e32 v209, v66, v122
	v_add_u32_e32 v210, 0xffffff00, v67
	v_add_u32_e32 v72, v206, v209
	v_add_u32_e32 v68, 0xffffff00, v72
	v_mad_i64_i32 v[68:69], s[38:39], v68, s8, v[160:161]
	v_readlane_b32 s22, v250, 19
	v_add_u32_e32 v66, v206, v210
	v_ashrrev_i32_e32 v67, 31, v66
	v_lshl_add_u64 v[68:69], v[68:69], 0, s[68:69]
	v_lshlrev_b64 v[66:67], 1, v[66:67]
	v_or_b32_e32 v74, v121, v122
	v_subrev_u32_e32 v75, s22, v160
	v_lshl_add_u64 v[70:71], v[162:163], 0, v[66:67]
	v_mul_u32_u24_e32 v76, 0x1a00, v74
	v_lshlrev_b32_e32 v77, 14, v74
	v_add_u32_e32 v76, v76, v75
	v_add_u32_e32 v77, v77, v75
	v_sub_co_u32_e32 v68, vcc, v68, v76
	s_nop 1
	v_subbrev_co_u32_e32 v69, vcc, 0, v69, vcc
	v_sub_co_u32_e32 v70, vcc, v70, v77
	s_nop 1
	v_subbrev_co_u32_e32 v71, vcc, 0, v71, vcc
	v_mov_b32_e32 v160, v76
	v_readfirstlane_b32 s98, v68
	v_readfirstlane_b32 s99, v69
	v_readfirstlane_b32 s100, v70
	v_readfirstlane_b32 s101, v71
	v_readfirstlane_b32 s87, v177
	v_add_u32_e32 v161, 0x1a000, v76
	v_add_u32_e32 v162, 0x34000, v76
	v_add_u32_e32 v163, 0x4e000, v76
	v_mov_b32_e32 v164, v77
	v_add_u32_e32 v165, 0x40000, v77
	v_add_u32_e32 v166, 0x80000, v77
	v_add_u32_e32 v167, 0xc0000, v77
	s_movk_i32 s64, 0x2000
	s_mov_b32 s65, 0
	s_mov_b64 s[40:41], 0
	s_mov_b64 s[42:43], s[4:5]
	s_branch .LBB0_279
	s_nop 0
	s_nop 0
	s_nop 0
	s_nop 0
	s_nop 0
	s_nop 0
	s_nop 0
	s_nop 0
	s_nop 0
	s_nop 0
	s_nop 0

; #define LAS __attribute__((address_space(3)))
; template <typename T> DI volatile LAS T* lds_fresh(volatile LAS T* q) { asm volatile("" : "+v"(q)); return q; }
; DI void xcd_barrier(const XcdBarrier& b) {
;   asm volatile("s_waitcnt vmcnt(0)" ::: "memory");
;   __syncthreads();
;   if (tid_now(b.wv) == 0) {
;     unsigned* bar = b.bar;
;     __builtin_amdgcn_s_waitcnt(0);
;     volatile LAS unsigned* st = lds_fresh(b.st);
;     unsigned nloc = st[0], nx = st[1];
;     if (nloc == 0u) { xcd_barrier_complete(bar, b.x, nloc, nx); st[0] = nloc; st[1] = nx; }
.LBB0_340:
	s_or_b64 exec, exec, s[84:85]
	s_waitcnt vmcnt(0)
	s_barrier
	v_mbcnt_lo_u32_b32 v0, -1, 0
	v_mbcnt_hi_u32_b32 v0, -1, v0
	s_nop 0
	v_cmp_eq_u32_e32 vcc, s41, v0
	s_and_saveexec_b64 s[0:1], vcc
	v_readlane_b32 s22, v250, 30
	s_movk_i32 s24, 0x50
	s_cbranch_execz .LBB0_392
	v_mov_b32_e32 v3, 0x12010
	s_waitcnt vmcnt(0) expcnt(0) lgkmcnt(0)
	s_setprio 3
	ds_read_b32 v2, v3
	ds_read_b32 v0, v3 offset:4
	s_waitcnt lgkmcnt(1)
	v_cmp_eq_u32_e32 vcc, 0, v2
	s_and_saveexec_b64 s[2:3], vcc
	s_cbranch_execz .LBB0_356
	s_mov_b32 s18, 1
	s_branch .LBB0_344

; template <int EPI>
; DI void gemm_tile(const Params& p, int layer, int mt, int nt, u16* sm, int wv) {
;   const int tid = tid_now(wv), w = tid >> 6;
;   int lane = tid & 63, fr = lane & 15, fq = lane >> 4;
;   const u16* A = (EPI == 0) ? p.xg : p.y;
;   const u16* Bt = (EPI == 0) ? p.wtin + (size_t)layer * DIN * 1024 : p.wtout + (size_t)layer * 1024 * 1024;
;   const int m0 = mt * 256, n0 = nt * 128;
;   const char* abase = (const char*)(A + (size_t)m0 * 1024);
;   const char* bbase = (const char*)(Bt + (size_t)n0 * 1024);
; __global__ void __launch_bounds__(256, 2) hymba_mega(Params p) {
;     ...
;     xcd_barrier(gb);
;     for (int u = lb; u < 8 * 8; u += nxb) gemm_tile<1>(p, layer, xcd + 8 * (u & 7), u >> 3, sm, wv);
.LBB0_392:
	s_setprio 0
	s_or_b64 exec, exec, s[0:1]
	v_readlane_b32 s0, v250, 24
	v_readlane_b32 s1, v250, 25
	s_andn2_b64 vcc, exec, s[0:1]
	s_waitcnt lgkmcnt(0)
	s_barrier
	s_cbranch_vccnz .LBB0_471
	v_readlane_b32 s0, v250, 26
	s_mov_b32 s2, s0
	s_lshl_b32 s0, s0, 21
	v_readlane_b32 s1, v250, 27
	s_add_u32 s6, s58, s0
	s_addc_u32 s7, s59, 0
	s_mov_b32 s1, s25
	s_lshl_b32 s0, s2, 14
	s_lshl_b64 s[0:1], s[0:1], 2
	s_add_u32 s0, s92, s0
	s_addc_u32 s1, s93, s1
	s_add_u32 s0, s0, 0x10000
	s_addc_u32 s1, s1, 0
	v_readlane_b32 s16, v250, 23
	s_branch .LBB0_395

; #define LAS __attribute__((address_space(3)))
; template <typename T> DI volatile LAS T* lds_fresh(volatile LAS T* q) { asm volatile("" : "+v"(q)); return q; }
; DI void xcd_barrier(const XcdBarrier& b) {
;   asm volatile("s_waitcnt vmcnt(0)" ::: "memory");
;   __syncthreads();
;   if (tid_now(b.wv) == 0) {
;     unsigned* bar = b.bar;
;     __builtin_amdgcn_s_waitcnt(0);
;     volatile LAS unsigned* st = lds_fresh(b.st);
;     unsigned nloc = st[0], nx = st[1];
;     if (nloc == 0u) { xcd_barrier_complete(bar, b.x, nloc, nx); st[0] = nloc; st[1] = nx; }
.LBB0_471:
	s_waitcnt vmcnt(0)
	s_waitcnt lgkmcnt(0)
	s_barrier
	v_mbcnt_lo_u32_b32 v0, -1, 0
	v_mbcnt_hi_u32_b32 v0, -1, v0
	s_nop 0
	v_cmp_eq_u32_e32 vcc, s41, v0
	s_and_saveexec_b64 s[0:1], vcc
	s_cbranch_execz .LBB0_108
	v_mov_b32_e32 v3, 0x12010
	s_waitcnt vmcnt(0) expcnt(0) lgkmcnt(0)
	s_setprio 3
	ds_read_b32 v2, v3
	ds_read_b32 v0, v3 offset:4
	s_waitcnt lgkmcnt(1)
	v_cmp_eq_u32_e32 vcc, 0, v2
	s_and_saveexec_b64 s[2:3], vcc
	s_cbranch_execz .LBB0_487
	s_mov_b32 s18, 1
	s_branch .LBB0_475
